# K=1024 GEMM loop back-edge rotation: counter/pointer updates and next iteration's scalar set-up moved in front of the loop-back barrier
# baseline (speedup 1.0000x reference)
; #define PG8_STAGE(bufoff, gbase, voff) do { _Pragma("unroll") for (int _i = 0; _i < 2; ++_i) \
;         __builtin_amdgcn_global_load_lds((const unsigned*)((const char*)(gbase) + (voff)[_i]), (PG8_LAS unsigned*)(lds + (bufoff) + ldsw + _i * 8192), 16, 0, 0); } while (0)
; #define PG8_LDA(dst, b, h) do { _Pragma("unroll") for (int m = 0; m < 4; ++m) _Pragma("unroll") for (int k = 0; k < 2; ++k) dst[m][k] = *(const PG8_LAS bf16x8*)(lds + PG8_SA(b, h) + aoff + m * 2048 + k * 1024); } while (0)
; #define PG8_LDB(dst, b, h) do { _Pragma("unroll") for (int n = 0; n < 2; ++n) _Pragma("unroll") for (int k = 0; k < 2; ++k) dst[n][k] = *(const PG8_LAS bf16x8*)(lds + PG8_SB(b, h) + boff + n * 2048 + k * 1024); } while (0)
; #define PG8_WAIT_V(n) asm volatile("s_waitcnt vmcnt(" #n ")" ::: "memory")
; #define PG8_WAIT_L(n) asm volatile("s_waitcnt lgkmcnt(" #n ")" ::: "memory")
; #define PG8_BAR __builtin_amdgcn_s_barrier()
; #define PG8_SCHED __builtin_amdgcn_sched_barrier(0)
; template <class Epi, class Sched, bool ALIGN_EPI = false, bool SP2 = false>
; __device__ __forceinline__ void gemm_phase(PG8_LAS unsigned char* lds, const Gemm g, const Sched& S, const Epi& E, const int wave0) {
;     ...
;         const bool has_next = S.next(ui + 1, nxt);
;         const char* nA = has_next ? (const char*)g.A + (size_t)nxt.pm * tstep : cA; const char* nB = has_next ? (const char*)g.Bt + (size_t)nxt.pn * tstep : cB;
;         for (int t = 0; t < nt; t += 2) {
;             const bool last = (t == nt - 2);
;             const char* a1 = cA + (size_t)(t + 1) * kstep;
;             const char* a2 = last ? nA : cA + (size_t)(t + 2) * kstep; const char* b2 = last ? nB : cB + (size_t)(t + 2) * kstep;
;             const char* a3 = a2 + kstep; const char* b3 = b2 + kstep;
;             if (last && has_next) S.a_ready(nxt);
;             if constexpr (SP2) {
;             PG8_LDB(B0, 0, 0); PG8_LDB(B1, 0, 1); PG8_SCHED; PG8_LDA(At, 0, 0); PG8_STAGE(PG8_SA(1, 1), a1 + hstep, voffA);
;             PG8_WAIT_V(8); PG8_WAIT_L(0); PG8_BAR; PG8_MMA(0, 0, At, B0); PG8_MMA(0, 1, At, B1); PG8_BAR; PG8_SCHED;
;             PG8_LDA(At, 0, 1); PG8_STAGE(PG8_SB(0, 0), b2, voffB); PG8_STAGE(PG8_SB(0, 1), b2 + hstep, voffB); PG8_STAGE(PG8_SA(0, 0), a2, voffA);
;             PG8_WAIT_V(8); PG8_WAIT_L(0); PG8_BAR; PG8_MMA(1, 0, At, B0); PG8_MMA(1, 1, At, B1); PG8_BAR; PG8_SCHED;
.LBB0_1139:
	s_ashr_i32 s49, s48, 31
	s_lshl_b64 s[18:19], s[48:49], 19
	s_add_u32 s50, s36, s18
	s_addc_u32 s51, s37, s19
	s_and_b64 s[18:19], s[6:7], exec
	s_cselect_b32 s9, s51, s11
	s_cselect_b32 s49, s50, s10
	s_ashr_i32 s47, s46, 31
	s_lshl_b64 s[18:19], s[46:47], 19
	s_add_u32 s52, s38, s18
	s_addc_u32 s53, s39, s19
	s_and_b64 s[18:19], s[6:7], exec
	s_cselect_b32 s47, s53, s57
	s_cselect_b32 s60, s52, s56
	s_add_u32 s10, s10, 0x40080
	s_addc_u32 s11, s11, 0
	s_add_u32 s61, s56, 0x100
	s_addc_u32 s62, s57, 0
	s_mov_b32 s63, -2
	global_load_dwordx4 v[192:195], v215, s[40:41] offset:1024
	global_load_dwordx4 v[196:199], v215, s[40:41] offset:1064
	global_load_dwordx4 v[200:203], v215, s[40:41] offset:1048
	s_waitcnt lgkmcnt(0)
	s_add_u32 s18, s10, 0xfffc0080
	s_addc_u32 s19, s11, -1
	s_add_i32 s64, 0, 0x10000
	s_cmp_eq_u32 s63, 12
	s_cselect_b32 s59, s9, s19
	s_cselect_b32 s58, s49, s18
	s_cselect_b32 s57, s47, s62
	s_cselect_b32 s56, s60, s61
	s_add_i32 s65, 0, 0x14000
	v_add_u32_e32 v140, s64, v247
	v_add_u32_e32 v156, s65, v247
	ds_read_b128 v[64:67], v140
	ds_read_b128 v[68:71], v140 offset:1024
	ds_read_b128 v[136:139], v140 offset:2048
	ds_read_b128 v[140:143], v140 offset:3072
	ds_read_b128 v[144:147], v156
	ds_read_b128 v[148:151], v156 offset:1024
	ds_read_b128 v[152:155], v156 offset:2048
	ds_read_b128 v[156:159], v156 offset:3072
	s_add_i32 m0, s33, 0xc000
	ds_read_b128 v[160:163], v245
	ds_read_b128 v[164:167], v245 offset:1024
	ds_read_b128 v[168:171], v245 offset:2048
	ds_read_b128 v[172:175], v245 offset:3072
	ds_read_b128 v[176:179], v245 offset:4096
	ds_read_b128 v[180:183], v245 offset:5120
	ds_read_b128 v[184:187], v245 offset:6144
	ds_read_b128 v[188:191], v245 offset:7168
	global_load_lds_dwordx4 v224, s[10:11]
	s_add_i32 m0, s33, 0xe000
	s_nop 0
	global_load_lds_dwordx4 v226, s[10:11]
	s_waitcnt vmcnt(8)
	s_waitcnt lgkmcnt(0)
	s_barrier
	s_setprio 1
	v_mfma_f32_16x16x32_bf16 v[132:135], v[64:67], v[160:163], 0
	v_mfma_f32_16x16x32_bf16 v[128:131], v[136:139], v[160:163], 0
	v_mfma_f32_16x16x32_bf16 v[116:119], v[64:67], v[168:171], 0
	v_mfma_f32_16x16x32_bf16 v[108:111], v[136:139], v[168:171], 0
	v_mfma_f32_16x16x32_bf16 v[100:103], v[64:67], v[176:179], 0
	v_mfma_f32_16x16x32_bf16 v[92:95], v[136:139], v[176:179], 0
	v_mfma_f32_16x16x32_bf16 v[84:87], v[64:67], v[184:187], 0
	v_mfma_f32_16x16x32_bf16 v[76:79], v[136:139], v[184:187], 0
	v_mfma_f32_16x16x32_bf16 v[132:135], v[68:71], v[164:167], v[132:135]
	v_mfma_f32_16x16x32_bf16 v[128:131], v[140:143], v[164:167], v[128:131]
	v_mfma_f32_16x16x32_bf16 v[116:119], v[68:71], v[172:175], v[116:119]
	v_mfma_f32_16x16x32_bf16 v[108:111], v[140:143], v[172:175], v[108:111]
	v_mfma_f32_16x16x32_bf16 v[100:103], v[68:71], v[180:183], v[100:103]
	v_mfma_f32_16x16x32_bf16 v[92:95], v[140:143], v[180:183], v[92:95]
	v_mfma_f32_16x16x32_bf16 v[84:87], v[68:71], v[188:191], v[84:87]
	v_mfma_f32_16x16x32_bf16 v[76:79], v[140:143], v[188:191], v[76:79]
	v_mfma_f32_16x16x32_bf16 v[124:127], v[144:147], v[160:163], 0
	v_mfma_f32_16x16x32_bf16 v[120:123], v[152:155], v[160:163], 0
	v_mfma_f32_16x16x32_bf16 v[112:115], v[144:147], v[168:171], 0
	v_mfma_f32_16x16x32_bf16 v[104:107], v[152:155], v[168:171], 0
	v_mfma_f32_16x16x32_bf16 v[96:99], v[144:147], v[176:179], 0
	v_mfma_f32_16x16x32_bf16 v[88:91], v[152:155], v[176:179], 0
	v_mfma_f32_16x16x32_bf16 v[80:83], v[144:147], v[184:187], 0
	v_mfma_f32_16x16x32_bf16 v[72:75], v[152:155], v[184:187], 0
	v_mfma_f32_16x16x32_bf16 v[124:127], v[148:151], v[164:167], v[124:127]
	v_mfma_f32_16x16x32_bf16 v[120:123], v[156:159], v[164:167], v[120:123]
	v_mfma_f32_16x16x32_bf16 v[112:115], v[148:151], v[172:175], v[112:115]
	v_mfma_f32_16x16x32_bf16 v[104:107], v[156:159], v[172:175], v[104:107]
	v_mfma_f32_16x16x32_bf16 v[96:99], v[148:151], v[180:183], v[96:99]
	v_mfma_f32_16x16x32_bf16 v[88:91], v[156:159], v[180:183], v[88:91]
	v_mfma_f32_16x16x32_bf16 v[80:83], v[148:151], v[188:191], v[80:83]
	v_mfma_f32_16x16x32_bf16 v[72:75], v[156:159], v[188:191], v[72:75]
	s_setprio 0
	s_barrier
	s_add_i32 s18, s64, s95
	s_mov_b32 m0, s18
	ds_read_b128 v[160:163], v245 offset:16384
	ds_read_b128 v[164:167], v245 offset:17408
	ds_read_b128 v[168:171], v245 offset:18432
	ds_read_b128 v[172:175], v245 offset:19456
	ds_read_b128 v[176:179], v245 offset:20480
	ds_read_b128 v[180:183], v245 offset:21504
	ds_read_b128 v[184:187], v245 offset:22528
	ds_read_b128 v[188:191], v245 offset:23552
	global_load_lds_dwordx4 v218, s[56:57]
	s_add_i32 m0, s18, 0x2000
	s_add_u32 s18, s56, 0x40000
	s_addc_u32 s19, s57, 0
	s_add_i32 s64, s65, s95
	global_load_lds_dwordx4 v222, s[56:57]
	s_mov_b32 m0, s64
	s_nop 0
	global_load_lds_dwordx4 v218, s[18:19]
	s_add_i32 m0, s64, 0x2000
	s_nop 0
	global_load_lds_dwordx4 v222, s[18:19]
	s_mov_b32 m0, s33
	s_nop 0
	global_load_lds_dwordx4 v216, s[58:59]
	s_mov_b32 m0, s82
	s_nop 0
	global_load_lds_dwordx4 v220, s[58:59]
	s_waitcnt vmcnt(8)
	s_waitcnt lgkmcnt(0)
	s_barrier
; #define PG8_STAGE(bufoff, gbase, voff) do { _Pragma("unroll") for (int _i = 0; _i < 2; ++_i) \
;         __builtin_amdgcn_global_load_lds((const unsigned*)((const char*)(gbase) + (voff)[_i]), (PG8_LAS unsigned*)(lds + (bufoff) + ldsw + _i * 8192), 16, 0, 0); } while (0)
; #define PG8_LDA(dst, b, h) do { _Pragma("unroll") for (int m = 0; m < 4; ++m) _Pragma("unroll") for (int k = 0; k < 2; ++k) dst[m][k] = *(const PG8_LAS bf16x8*)(lds + PG8_SA(b, h) + aoff + m * 2048 + k * 1024); } while (0)
; #define PG8_LDB(dst, b, h) do { _Pragma("unroll") for (int n = 0; n < 2; ++n) _Pragma("unroll") for (int k = 0; k < 2; ++k) dst[n][k] = *(const PG8_LAS bf16x8*)(lds + PG8_SB(b, h) + boff + n * 2048 + k * 1024); } while (0)
; #define PG8_MMA(ai, bj, At, Bt) do { __builtin_amdgcn_s_setprio(1); _Pragma("unroll") for (int m = 0; m < 4; ++m) _Pragma("unroll") for (int n = 0; n < 2; ++n) _Pragma("unroll") for (int k = 0; k < 2; ++k) \
;         acc[ai][bj][m][n] = __builtin_amdgcn_mfma_f32_16x16x32_bf16(Bt[n][k], At[m][k], acc[ai][bj][m][n], 0, 0, 0); __builtin_amdgcn_s_setprio(0); } while (0)
; #define PG8_WAIT_V(n) asm volatile("s_waitcnt vmcnt(" #n ")" ::: "memory")
; #define PG8_WAIT_L(n) asm volatile("s_waitcnt lgkmcnt(" #n ")" ::: "memory")
; #define PG8_BAR __builtin_amdgcn_s_barrier()
; #define PG8_SCHED __builtin_amdgcn_sched_barrier(0)
; template <class Epi, class Sched, bool ALIGN_EPI = false, bool SP2 = false>
; __device__ __forceinline__ void gemm_phase(PG8_LAS unsigned char* lds, const Gemm g, const Sched& S, const Epi& E, const int wave0) {
;     ...
;             PG8_WAIT_V(8); PG8_WAIT_L(0); PG8_BAR; PG8_MMA(1, 0, At, B0); PG8_MMA(1, 1, At, B1); PG8_BAR; PG8_SCHED;
;             PG8_LDB(B0, 1, 0); PG8_LDB(B1, 1, 1); PG8_SCHED; PG8_LDA(At, 1, 0); PG8_STAGE(PG8_SA(0, 1), a2 + hstep, voffA);
;             PG8_WAIT_V(8); PG8_WAIT_L(0); PG8_BAR; PG8_MMA(0, 0, At, B0); PG8_MMA(0, 1, At, B1); PG8_BAR; PG8_SCHED;
	s_setprio 1
	v_mfma_f32_16x16x32_bf16 v[60:63], v[64:67], v[160:163], 0
	v_mfma_f32_16x16x32_bf16 v[52:55], v[136:139], v[160:163], 0
	v_mfma_f32_16x16x32_bf16 v[44:47], v[64:67], v[168:171], 0
	v_mfma_f32_16x16x32_bf16 v[36:39], v[136:139], v[168:171], 0
	v_mfma_f32_16x16x32_bf16 v[28:31], v[64:67], v[176:179], 0
	v_mfma_f32_16x16x32_bf16 v[20:23], v[136:139], v[176:179], 0
	v_mfma_f32_16x16x32_bf16 v[12:15], v[64:67], v[184:187], 0
	v_mfma_f32_16x16x32_bf16 v[4:7], v[136:139], v[184:187], 0
	v_mfma_f32_16x16x32_bf16 v[60:63], v[68:71], v[164:167], v[60:63]
	v_mfma_f32_16x16x32_bf16 v[52:55], v[140:143], v[164:167], v[52:55]
	v_mfma_f32_16x16x32_bf16 v[44:47], v[68:71], v[172:175], v[44:47]
	v_mfma_f32_16x16x32_bf16 v[36:39], v[140:143], v[172:175], v[36:39]
	v_mfma_f32_16x16x32_bf16 v[28:31], v[68:71], v[180:183], v[28:31]
	v_mfma_f32_16x16x32_bf16 v[20:23], v[140:143], v[180:183], v[20:23]
	v_mfma_f32_16x16x32_bf16 v[12:15], v[68:71], v[188:191], v[12:15]
	v_mfma_f32_16x16x32_bf16 v[4:7], v[140:143], v[188:191], v[4:7]
	v_mfma_f32_16x16x32_bf16 v[56:59], v[144:147], v[160:163], 0
	v_mfma_f32_16x16x32_bf16 v[48:51], v[152:155], v[160:163], 0
	v_mfma_f32_16x16x32_bf16 v[40:43], v[144:147], v[168:171], 0
	v_mfma_f32_16x16x32_bf16 v[32:35], v[152:155], v[168:171], 0
	v_mfma_f32_16x16x32_bf16 v[24:27], v[144:147], v[176:179], 0
	v_mfma_f32_16x16x32_bf16 v[16:19], v[152:155], v[176:179], 0
	v_mfma_f32_16x16x32_bf16 v[8:11], v[144:147], v[184:187], 0
	v_mfma_f32_16x16x32_bf16 v[0:3], v[152:155], v[184:187], 0
	v_mfma_f32_16x16x32_bf16 v[56:59], v[148:151], v[164:167], v[56:59]
	v_mfma_f32_16x16x32_bf16 v[48:51], v[156:159], v[164:167], v[48:51]
	v_mfma_f32_16x16x32_bf16 v[40:43], v[148:151], v[172:175], v[40:43]
	v_mfma_f32_16x16x32_bf16 v[32:35], v[156:159], v[172:175], v[32:35]
	v_mfma_f32_16x16x32_bf16 v[24:27], v[148:151], v[180:183], v[24:27]
	v_mfma_f32_16x16x32_bf16 v[16:19], v[156:159], v[180:183], v[16:19]
	v_mfma_f32_16x16x32_bf16 v[8:11], v[148:151], v[188:191], v[8:11]
	v_mfma_f32_16x16x32_bf16 v[0:3], v[156:159], v[188:191], v[0:3]
	s_setprio 0
	s_barrier
	s_add_i32 s64, 0, 0x18000
	s_add_i32 s65, 0, 0x1c000
	v_add_u32_e32 v140, s64, v247
	v_add_u32_e32 v156, s65, v247
	ds_read_b128 v[64:67], v140
	ds_read_b128 v[68:71], v140 offset:1024
	ds_read_b128 v[136:139], v140 offset:2048
	ds_read_b128 v[140:143], v140 offset:3072
	ds_read_b128 v[144:147], v156
	ds_read_b128 v[148:151], v156 offset:1024
	ds_read_b128 v[152:155], v156 offset:2048
	ds_read_b128 v[156:159], v156 offset:3072
	s_add_u32 s18, s58, 0x40000
	s_addc_u32 s19, s59, 0
	s_mov_b32 m0, s16
	ds_read_b128 v[160:163], v245 offset:32768
	ds_read_b128 v[164:167], v245 offset:33792
	ds_read_b128 v[168:171], v245 offset:34816
	ds_read_b128 v[172:175], v245 offset:35840
	ds_read_b128 v[176:179], v245 offset:36864
	ds_read_b128 v[180:183], v245 offset:37888
	ds_read_b128 v[184:187], v245 offset:38912
	ds_read_b128 v[188:191], v245 offset:39936
	global_load_lds_dwordx4 v216, s[18:19]
	s_mov_b32 m0, s83
	s_nop 0
	global_load_lds_dwordx4 v220, s[18:19]
	s_waitcnt vmcnt(8)
	s_waitcnt lgkmcnt(0)
	s_barrier
	s_setprio 1
	v_mfma_f32_16x16x32_bf16 v[132:135], v[64:67], v[160:163], v[132:135]
	v_mfma_f32_16x16x32_bf16 v[128:131], v[136:139], v[160:163], v[128:131]
	v_mfma_f32_16x16x32_bf16 v[116:119], v[64:67], v[168:171], v[116:119]
	v_mfma_f32_16x16x32_bf16 v[108:111], v[136:139], v[168:171], v[108:111]
	v_mfma_f32_16x16x32_bf16 v[100:103], v[64:67], v[176:179], v[100:103]
	v_mfma_f32_16x16x32_bf16 v[92:95], v[136:139], v[176:179], v[92:95]
	v_mfma_f32_16x16x32_bf16 v[84:87], v[64:67], v[184:187], v[84:87]
	v_mfma_f32_16x16x32_bf16 v[76:79], v[136:139], v[184:187], v[76:79]
	v_mfma_f32_16x16x32_bf16 v[132:135], v[68:71], v[164:167], v[132:135]
	v_mfma_f32_16x16x32_bf16 v[128:131], v[140:143], v[164:167], v[128:131]
	v_mfma_f32_16x16x32_bf16 v[116:119], v[68:71], v[172:175], v[116:119]
	v_mfma_f32_16x16x32_bf16 v[108:111], v[140:143], v[172:175], v[108:111]
	v_mfma_f32_16x16x32_bf16 v[100:103], v[68:71], v[180:183], v[100:103]
	v_mfma_f32_16x16x32_bf16 v[92:95], v[140:143], v[180:183], v[92:95]
	v_mfma_f32_16x16x32_bf16 v[84:87], v[68:71], v[188:191], v[84:87]
	v_mfma_f32_16x16x32_bf16 v[76:79], v[140:143], v[188:191], v[76:79]
	v_mfma_f32_16x16x32_bf16 v[124:127], v[144:147], v[160:163], v[124:127]
	v_mfma_f32_16x16x32_bf16 v[120:123], v[152:155], v[160:163], v[120:123]
	v_mfma_f32_16x16x32_bf16 v[112:115], v[144:147], v[168:171], v[112:115]
	v_mfma_f32_16x16x32_bf16 v[104:107], v[152:155], v[168:171], v[104:107]
	v_mfma_f32_16x16x32_bf16 v[96:99], v[144:147], v[176:179], v[96:99]
	v_mfma_f32_16x16x32_bf16 v[88:91], v[152:155], v[176:179], v[88:91]
	v_mfma_f32_16x16x32_bf16 v[80:83], v[144:147], v[184:187], v[80:83]
	v_mfma_f32_16x16x32_bf16 v[72:75], v[152:155], v[184:187], v[72:75]
	v_mfma_f32_16x16x32_bf16 v[124:127], v[148:151], v[164:167], v[124:127]
	v_mfma_f32_16x16x32_bf16 v[120:123], v[156:159], v[164:167], v[120:123]
	v_mfma_f32_16x16x32_bf16 v[112:115], v[148:151], v[172:175], v[112:115]
	v_mfma_f32_16x16x32_bf16 v[104:107], v[156:159], v[172:175], v[104:107]
	v_mfma_f32_16x16x32_bf16 v[96:99], v[148:151], v[180:183], v[96:99]
	v_mfma_f32_16x16x32_bf16 v[88:91], v[156:159], v[180:183], v[88:91]
	v_mfma_f32_16x16x32_bf16 v[80:83], v[148:151], v[188:191], v[80:83]
	v_mfma_f32_16x16x32_bf16 v[72:75], v[156:159], v[188:191], v[72:75]
	s_setprio 0
	s_barrier
; #define PG8_STAGE(bufoff, gbase, voff) do { _Pragma("unroll") for (int _i = 0; _i < 2; ++_i) \
;         __builtin_amdgcn_global_load_lds((const unsigned*)((const char*)(gbase) + (voff)[_i]), (PG8_LAS unsigned*)(lds + (bufoff) + ldsw + _i * 8192), 16, 0, 0); } while (0)
; #define PG8_LDA(dst, b, h) do { _Pragma("unroll") for (int m = 0; m < 4; ++m) _Pragma("unroll") for (int k = 0; k < 2; ++k) dst[m][k] = *(const PG8_LAS bf16x8*)(lds + PG8_SA(b, h) + aoff + m * 2048 + k * 1024); } while (0)
; #define PG8_LDB(dst, b, h) do { _Pragma("unroll") for (int n = 0; n < 2; ++n) _Pragma("unroll") for (int k = 0; k < 2; ++k) dst[n][k] = *(const PG8_LAS bf16x8*)(lds + PG8_SB(b, h) + boff + n * 2048 + k * 1024); } while (0)
; #define PG8_MMA(ai, bj, At, Bt) do { __builtin_amdgcn_s_setprio(1); _Pragma("unroll") for (int m = 0; m < 4; ++m) _Pragma("unroll") for (int n = 0; n < 2; ++n) _Pragma("unroll") for (int k = 0; k < 2; ++k) \
;         acc[ai][bj][m][n] = __builtin_amdgcn_mfma_f32_16x16x32_bf16(Bt[n][k], At[m][k], acc[ai][bj][m][n], 0, 0, 0); __builtin_amdgcn_s_setprio(0); } while (0)
; #define PG8_WAIT_V(n) asm volatile("s_waitcnt vmcnt(" #n ")" ::: "memory")
; #define PG8_BAR __builtin_amdgcn_s_barrier()
; template <class Epi, class Sched, bool ALIGN_EPI = false, bool SP2 = false>
; __device__ __forceinline__ void gemm_phase(PG8_LAS unsigned char* lds, const Gemm g, const Sched& S, const Epi& E, const int wave0) {
;     ...
;         for (int t = 0; t < nt; t += 2) {
;             const bool last = (t == nt - 2);
;             const char* a1 = cA + (size_t)(t + 1) * kstep;
;             const char* a2 = last ? nA : cA + (size_t)(t + 2) * kstep; const char* b2 = last ? nB : cB + (size_t)(t + 2) * kstep;
;             const char* a3 = a2 + kstep; const char* b3 = b2 + kstep;
;             if (last && has_next) S.a_ready(nxt);
;             if constexpr (SP2) {
;             PG8_LDB(B0, 0, 0); PG8_LDB(B1, 0, 1); PG8_SCHED; PG8_LDA(At, 0, 0); PG8_STAGE(PG8_SA(1, 1), a1 + hstep, voffA);
;             PG8_WAIT_V(8); PG8_WAIT_L(0); PG8_BAR; PG8_MMA(0, 0, At, B0); PG8_MMA(0, 1, At, B1); PG8_BAR; PG8_SCHED;
;     ...
;             PG8_LDA(At, 1, 1); PG8_STAGE(PG8_SB(1, 0), b3, voffB); PG8_STAGE(PG8_SB(1, 1), b3 + hstep, voffB); PG8_STAGE(PG8_SA(1, 0), a3, voffA);
;             PG8_WAIT_V(8); PG8_WAIT_L(0); PG8_BAR; PG8_MMA(1, 0, At, B0); PG8_MMA(1, 1, At, B1); PG8_BAR; PG8_SCHED;
	s_add_i32 s18, s64, s95
	s_add_i32 m0, s18, 0xffffff80
	ds_read_b128 v[160:163], v245 offset:49152
	ds_read_b128 v[164:167], v245 offset:50176
	ds_read_b128 v[168:171], v245 offset:51200
	ds_read_b128 v[172:175], v245 offset:52224
	ds_read_b128 v[176:179], v245 offset:53248
	ds_read_b128 v[180:183], v245 offset:54272
	ds_read_b128 v[184:187], v245 offset:55296
	ds_read_b128 v[188:191], v245 offset:56320
	global_load_lds_dwordx4 v218, s[56:57] offset:128
	s_add_i32 m0, s18, 0x1f80
	s_add_u32 s18, s56, 0x40080
	s_addc_u32 s19, s57, 0
	global_load_lds_dwordx4 v222, s[56:57] offset:128
	s_add_i32 s56, s65, s95
	s_mov_b32 m0, s56
	s_nop 0
	global_load_lds_dwordx4 v218, s[18:19]
	s_add_i32 m0, s56, 0x2000
	s_nop 0
	global_load_lds_dwordx4 v222, s[18:19]
	s_add_i32 m0, s17, 0xffffff80
	s_nop 0
	global_load_lds_dwordx4 v216, s[58:59] offset:128
	s_add_i32 m0, s23, 0xffffff80
	s_nop 0
	global_load_lds_dwordx4 v220, s[58:59] offset:128
	s_waitcnt vmcnt(8)
	s_waitcnt lgkmcnt(0)
	s_barrier
	s_setprio 1
	v_mfma_f32_16x16x32_bf16 v[60:63], v[64:67], v[160:163], v[60:63]
	v_mfma_f32_16x16x32_bf16 v[52:55], v[136:139], v[160:163], v[52:55]
	v_mfma_f32_16x16x32_bf16 v[44:47], v[64:67], v[168:171], v[44:47]
	v_mfma_f32_16x16x32_bf16 v[36:39], v[136:139], v[168:171], v[36:39]
	v_mfma_f32_16x16x32_bf16 v[28:31], v[64:67], v[176:179], v[28:31]
	v_mfma_f32_16x16x32_bf16 v[20:23], v[136:139], v[176:179], v[20:23]
	v_mfma_f32_16x16x32_bf16 v[12:15], v[64:67], v[184:187], v[12:15]
	v_mfma_f32_16x16x32_bf16 v[4:7], v[136:139], v[184:187], v[4:7]
	v_mfma_f32_16x16x32_bf16 v[60:63], v[68:71], v[164:167], v[60:63]
	v_mfma_f32_16x16x32_bf16 v[52:55], v[140:143], v[164:167], v[52:55]
	v_mfma_f32_16x16x32_bf16 v[44:47], v[68:71], v[172:175], v[44:47]
	v_mfma_f32_16x16x32_bf16 v[36:39], v[140:143], v[172:175], v[36:39]
	v_mfma_f32_16x16x32_bf16 v[28:31], v[68:71], v[180:183], v[28:31]
	v_mfma_f32_16x16x32_bf16 v[20:23], v[140:143], v[180:183], v[20:23]
	v_mfma_f32_16x16x32_bf16 v[12:15], v[68:71], v[188:191], v[12:15]
	v_mfma_f32_16x16x32_bf16 v[4:7], v[140:143], v[188:191], v[4:7]
	v_mfma_f32_16x16x32_bf16 v[56:59], v[144:147], v[160:163], v[56:59]
	v_mfma_f32_16x16x32_bf16 v[48:51], v[152:155], v[160:163], v[48:51]
	v_mfma_f32_16x16x32_bf16 v[40:43], v[144:147], v[168:171], v[40:43]
	v_mfma_f32_16x16x32_bf16 v[32:35], v[152:155], v[168:171], v[32:35]
	v_mfma_f32_16x16x32_bf16 v[24:27], v[144:147], v[176:179], v[24:27]
	v_mfma_f32_16x16x32_bf16 v[16:19], v[152:155], v[176:179], v[16:19]
	v_mfma_f32_16x16x32_bf16 v[8:11], v[144:147], v[184:187], v[8:11]
	v_mfma_f32_16x16x32_bf16 v[0:3], v[152:155], v[184:187], v[0:3]
	v_mfma_f32_16x16x32_bf16 v[56:59], v[148:151], v[164:167], v[56:59]
	v_mfma_f32_16x16x32_bf16 v[48:51], v[156:159], v[164:167], v[48:51]
	v_mfma_f32_16x16x32_bf16 v[40:43], v[148:151], v[172:175], v[40:43]
	v_mfma_f32_16x16x32_bf16 v[32:35], v[156:159], v[172:175], v[32:35]
	v_mfma_f32_16x16x32_bf16 v[24:27], v[148:151], v[180:183], v[24:27]
	v_mfma_f32_16x16x32_bf16 v[16:19], v[156:159], v[180:183], v[16:19]
	v_mfma_f32_16x16x32_bf16 v[8:11], v[148:151], v[188:191], v[8:11]
	v_mfma_f32_16x16x32_bf16 v[0:3], v[156:159], v[188:191], v[0:3]
	s_setprio 0
	s_add_i32 s63, s63, 2
	s_add_u32 s10, s10, 0x100
	s_addc_u32 s11, s11, 0
	s_add_u32 s61, s61, 0x100
	s_addc_u32 s62, s62, 0
	s_add_u32 s18, s10, 0xfffc0080
	s_addc_u32 s19, s11, -1
	s_add_i32 s64, 0, 0x10000
	s_cmp_eq_u32 s63, 12
	s_cselect_b32 s59, s9, s19
	s_cselect_b32 s58, s49, s18
	s_cselect_b32 s57, s47, s62
	s_cselect_b32 s56, s60, s61
	s_add_i32 s65, 0, 0x14000
	v_add_u32_e32 v140, s64, v247
	v_add_u32_e32 v156, s65, v247
	s_barrier
.LBB0_1140:
	ds_read_b128 v[64:67], v140
	ds_read_b128 v[68:71], v140 offset:1024
	ds_read_b128 v[136:139], v140 offset:2048
	ds_read_b128 v[140:143], v140 offset:3072
	ds_read_b128 v[144:147], v156
	ds_read_b128 v[148:151], v156 offset:1024
	ds_read_b128 v[152:155], v156 offset:2048
	ds_read_b128 v[156:159], v156 offset:3072
	s_add_i32 m0, s33, 0xc000
	ds_read_b128 v[160:163], v245
	ds_read_b128 v[164:167], v245 offset:1024
	ds_read_b128 v[168:171], v245 offset:2048
	ds_read_b128 v[172:175], v245 offset:3072
	ds_read_b128 v[176:179], v245 offset:4096
	ds_read_b128 v[180:183], v245 offset:5120
	ds_read_b128 v[184:187], v245 offset:6144
	ds_read_b128 v[188:191], v245 offset:7168
	global_load_lds_dwordx4 v224, s[10:11]
	s_add_i32 m0, s33, 0xe000
	s_nop 0
	global_load_lds_dwordx4 v226, s[10:11]
	s_waitcnt vmcnt(8)
	s_waitcnt lgkmcnt(0)
	s_barrier
; #define PG8_STAGE(bufoff, gbase, voff) do { _Pragma("unroll") for (int _i = 0; _i < 2; ++_i) \
;         __builtin_amdgcn_global_load_lds((const unsigned*)((const char*)(gbase) + (voff)[_i]), (PG8_LAS unsigned*)(lds + (bufoff) + ldsw + _i * 8192), 16, 0, 0); } while (0)
; #define PG8_LDA(dst, b, h) do { _Pragma("unroll") for (int m = 0; m < 4; ++m) _Pragma("unroll") for (int k = 0; k < 2; ++k) dst[m][k] = *(const PG8_LAS bf16x8*)(lds + PG8_SA(b, h) + aoff + m * 2048 + k * 1024); } while (0)
; #define PG8_MMA(ai, bj, At, Bt) do { __builtin_amdgcn_s_setprio(1); _Pragma("unroll") for (int m = 0; m < 4; ++m) _Pragma("unroll") for (int n = 0; n < 2; ++n) _Pragma("unroll") for (int k = 0; k < 2; ++k) \
;         acc[ai][bj][m][n] = __builtin_amdgcn_mfma_f32_16x16x32_bf16(Bt[n][k], At[m][k], acc[ai][bj][m][n], 0, 0, 0); __builtin_amdgcn_s_setprio(0); } while (0)
; #define PG8_WAIT_V(n) asm volatile("s_waitcnt vmcnt(" #n ")" ::: "memory")
; #define PG8_WAIT_L(n) asm volatile("s_waitcnt lgkmcnt(" #n ")" ::: "memory")
; #define PG8_BAR __builtin_amdgcn_s_barrier()
; #define PG8_SCHED __builtin_amdgcn_sched_barrier(0)
; template <class Epi, class Sched, bool ALIGN_EPI = false, bool SP2 = false>
; __device__ __forceinline__ void gemm_phase(PG8_LAS unsigned char* lds, const Gemm g, const Sched& S, const Epi& E, const int wave0) {
;     ...
;             PG8_WAIT_V(8); PG8_WAIT_L(0); PG8_BAR; PG8_MMA(0, 0, At, B0); PG8_MMA(0, 1, At, B1); PG8_BAR; PG8_SCHED;
;             PG8_LDA(At, 0, 1); PG8_STAGE(PG8_SB(0, 0), b2, voffB); PG8_STAGE(PG8_SB(0, 1), b2 + hstep, voffB); PG8_STAGE(PG8_SA(0, 0), a2, voffA);
;             PG8_WAIT_V(8); PG8_WAIT_L(0); PG8_BAR; PG8_MMA(1, 0, At, B0); PG8_MMA(1, 1, At, B1); PG8_BAR; PG8_SCHED;
	s_setprio 1
	v_mfma_f32_16x16x32_bf16 v[132:135], v[64:67], v[160:163], v[132:135]
	v_mfma_f32_16x16x32_bf16 v[128:131], v[136:139], v[160:163], v[128:131]
	v_mfma_f32_16x16x32_bf16 v[116:119], v[64:67], v[168:171], v[116:119]
	v_mfma_f32_16x16x32_bf16 v[108:111], v[136:139], v[168:171], v[108:111]
	v_mfma_f32_16x16x32_bf16 v[100:103], v[64:67], v[176:179], v[100:103]
	v_mfma_f32_16x16x32_bf16 v[92:95], v[136:139], v[176:179], v[92:95]
	v_mfma_f32_16x16x32_bf16 v[84:87], v[64:67], v[184:187], v[84:87]
	v_mfma_f32_16x16x32_bf16 v[76:79], v[136:139], v[184:187], v[76:79]
	v_mfma_f32_16x16x32_bf16 v[132:135], v[68:71], v[164:167], v[132:135]
	v_mfma_f32_16x16x32_bf16 v[128:131], v[140:143], v[164:167], v[128:131]
	v_mfma_f32_16x16x32_bf16 v[116:119], v[68:71], v[172:175], v[116:119]
	v_mfma_f32_16x16x32_bf16 v[108:111], v[140:143], v[172:175], v[108:111]
	v_mfma_f32_16x16x32_bf16 v[100:103], v[68:71], v[180:183], v[100:103]
	v_mfma_f32_16x16x32_bf16 v[92:95], v[140:143], v[180:183], v[92:95]
	v_mfma_f32_16x16x32_bf16 v[84:87], v[68:71], v[188:191], v[84:87]
	v_mfma_f32_16x16x32_bf16 v[76:79], v[140:143], v[188:191], v[76:79]
	v_mfma_f32_16x16x32_bf16 v[124:127], v[144:147], v[160:163], v[124:127]
	v_mfma_f32_16x16x32_bf16 v[120:123], v[152:155], v[160:163], v[120:123]
	v_mfma_f32_16x16x32_bf16 v[112:115], v[144:147], v[168:171], v[112:115]
	v_mfma_f32_16x16x32_bf16 v[104:107], v[152:155], v[168:171], v[104:107]
	v_mfma_f32_16x16x32_bf16 v[96:99], v[144:147], v[176:179], v[96:99]
	v_mfma_f32_16x16x32_bf16 v[88:91], v[152:155], v[176:179], v[88:91]
	v_mfma_f32_16x16x32_bf16 v[80:83], v[144:147], v[184:187], v[80:83]
	v_mfma_f32_16x16x32_bf16 v[72:75], v[152:155], v[184:187], v[72:75]
	v_mfma_f32_16x16x32_bf16 v[124:127], v[148:151], v[164:167], v[124:127]
	v_mfma_f32_16x16x32_bf16 v[120:123], v[156:159], v[164:167], v[120:123]
	v_mfma_f32_16x16x32_bf16 v[112:115], v[148:151], v[172:175], v[112:115]
	v_mfma_f32_16x16x32_bf16 v[104:107], v[156:159], v[172:175], v[104:107]
	v_mfma_f32_16x16x32_bf16 v[96:99], v[148:151], v[180:183], v[96:99]
	v_mfma_f32_16x16x32_bf16 v[88:91], v[156:159], v[180:183], v[88:91]
	v_mfma_f32_16x16x32_bf16 v[80:83], v[148:151], v[188:191], v[80:83]
	v_mfma_f32_16x16x32_bf16 v[72:75], v[156:159], v[188:191], v[72:75]
	s_setprio 0
	s_barrier
	s_add_i32 s18, s64, s95
	s_mov_b32 m0, s18
	ds_read_b128 v[160:163], v245 offset:16384
	ds_read_b128 v[164:167], v245 offset:17408
	ds_read_b128 v[168:171], v245 offset:18432
	ds_read_b128 v[172:175], v245 offset:19456
	ds_read_b128 v[176:179], v245 offset:20480
	ds_read_b128 v[180:183], v245 offset:21504
	ds_read_b128 v[184:187], v245 offset:22528
	ds_read_b128 v[188:191], v245 offset:23552
	global_load_lds_dwordx4 v218, s[56:57]
	s_add_i32 m0, s18, 0x2000
	s_add_u32 s18, s56, 0x40000
	s_addc_u32 s19, s57, 0
	s_add_i32 s64, s65, s95
	global_load_lds_dwordx4 v222, s[56:57]
	s_mov_b32 m0, s64
	s_nop 0
	global_load_lds_dwordx4 v218, s[18:19]
	s_add_i32 m0, s64, 0x2000
	s_nop 0
	global_load_lds_dwordx4 v222, s[18:19]
	s_mov_b32 m0, s33
	s_nop 0
	global_load_lds_dwordx4 v216, s[58:59]
	s_mov_b32 m0, s82
	s_nop 0
	global_load_lds_dwordx4 v220, s[58:59]
	s_waitcnt vmcnt(8)
	s_waitcnt lgkmcnt(0)
	s_barrier
	s_setprio 1
	v_mfma_f32_16x16x32_bf16 v[60:63], v[64:67], v[160:163], v[60:63]
	v_mfma_f32_16x16x32_bf16 v[52:55], v[136:139], v[160:163], v[52:55]
	v_mfma_f32_16x16x32_bf16 v[44:47], v[64:67], v[168:171], v[44:47]
	v_mfma_f32_16x16x32_bf16 v[36:39], v[136:139], v[168:171], v[36:39]
	v_mfma_f32_16x16x32_bf16 v[28:31], v[64:67], v[176:179], v[28:31]
	v_mfma_f32_16x16x32_bf16 v[20:23], v[136:139], v[176:179], v[20:23]
	v_mfma_f32_16x16x32_bf16 v[12:15], v[64:67], v[184:187], v[12:15]
	v_mfma_f32_16x16x32_bf16 v[4:7], v[136:139], v[184:187], v[4:7]
	v_mfma_f32_16x16x32_bf16 v[60:63], v[68:71], v[164:167], v[60:63]
	v_mfma_f32_16x16x32_bf16 v[52:55], v[140:143], v[164:167], v[52:55]
	v_mfma_f32_16x16x32_bf16 v[44:47], v[68:71], v[172:175], v[44:47]
	v_mfma_f32_16x16x32_bf16 v[36:39], v[140:143], v[172:175], v[36:39]
	v_mfma_f32_16x16x32_bf16 v[28:31], v[68:71], v[180:183], v[28:31]
	v_mfma_f32_16x16x32_bf16 v[20:23], v[140:143], v[180:183], v[20:23]
	v_mfma_f32_16x16x32_bf16 v[12:15], v[68:71], v[188:191], v[12:15]
	v_mfma_f32_16x16x32_bf16 v[4:7], v[140:143], v[188:191], v[4:7]
	v_mfma_f32_16x16x32_bf16 v[56:59], v[144:147], v[160:163], v[56:59]
	v_mfma_f32_16x16x32_bf16 v[48:51], v[152:155], v[160:163], v[48:51]
	v_mfma_f32_16x16x32_bf16 v[40:43], v[144:147], v[168:171], v[40:43]
	v_mfma_f32_16x16x32_bf16 v[32:35], v[152:155], v[168:171], v[32:35]
	v_mfma_f32_16x16x32_bf16 v[24:27], v[144:147], v[176:179], v[24:27]
	v_mfma_f32_16x16x32_bf16 v[16:19], v[152:155], v[176:179], v[16:19]
	v_mfma_f32_16x16x32_bf16 v[8:11], v[144:147], v[184:187], v[8:11]
	v_mfma_f32_16x16x32_bf16 v[0:3], v[152:155], v[184:187], v[0:3]
	v_mfma_f32_16x16x32_bf16 v[56:59], v[148:151], v[164:167], v[56:59]
	v_mfma_f32_16x16x32_bf16 v[48:51], v[156:159], v[164:167], v[48:51]
	v_mfma_f32_16x16x32_bf16 v[40:43], v[148:151], v[172:175], v[40:43]
	v_mfma_f32_16x16x32_bf16 v[32:35], v[156:159], v[172:175], v[32:35]
	v_mfma_f32_16x16x32_bf16 v[24:27], v[148:151], v[180:183], v[24:27]
	v_mfma_f32_16x16x32_bf16 v[16:19], v[156:159], v[180:183], v[16:19]
	v_mfma_f32_16x16x32_bf16 v[8:11], v[148:151], v[188:191], v[8:11]
	v_mfma_f32_16x16x32_bf16 v[0:3], v[156:159], v[188:191], v[0:3]
	s_setprio 0
	s_barrier
; #define PG8_STAGE(bufoff, gbase, voff) do { _Pragma("unroll") for (int _i = 0; _i < 2; ++_i) \
;         __builtin_amdgcn_global_load_lds((const unsigned*)((const char*)(gbase) + (voff)[_i]), (PG8_LAS unsigned*)(lds + (bufoff) + ldsw + _i * 8192), 16, 0, 0); } while (0)
; #define PG8_LDA(dst, b, h) do { _Pragma("unroll") for (int m = 0; m < 4; ++m) _Pragma("unroll") for (int k = 0; k < 2; ++k) dst[m][k] = *(const PG8_LAS bf16x8*)(lds + PG8_SA(b, h) + aoff + m * 2048 + k * 1024); } while (0)
; #define PG8_LDB(dst, b, h) do { _Pragma("unroll") for (int n = 0; n < 2; ++n) _Pragma("unroll") for (int k = 0; k < 2; ++k) dst[n][k] = *(const PG8_LAS bf16x8*)(lds + PG8_SB(b, h) + boff + n * 2048 + k * 1024); } while (0)
; #define PG8_MMA(ai, bj, At, Bt) do { __builtin_amdgcn_s_setprio(1); _Pragma("unroll") for (int m = 0; m < 4; ++m) _Pragma("unroll") for (int n = 0; n < 2; ++n) _Pragma("unroll") for (int k = 0; k < 2; ++k) \
;         acc[ai][bj][m][n] = __builtin_amdgcn_mfma_f32_16x16x32_bf16(Bt[n][k], At[m][k], acc[ai][bj][m][n], 0, 0, 0); __builtin_amdgcn_s_setprio(0); } while (0)
; #define PG8_WAIT_V(n) asm volatile("s_waitcnt vmcnt(" #n ")" ::: "memory")
; #define PG8_WAIT_L(n) asm volatile("s_waitcnt lgkmcnt(" #n ")" ::: "memory")
; #define PG8_BAR __builtin_amdgcn_s_barrier()
; #define PG8_SCHED __builtin_amdgcn_sched_barrier(0)
; template <class Epi, class Sched, bool ALIGN_EPI = false, bool SP2 = false>
; __device__ __forceinline__ void gemm_phase(PG8_LAS unsigned char* lds, const Gemm g, const Sched& S, const Epi& E, const int wave0) {
;     ...
;         for (int t = 0; t < nt; t += 2) {
;             const bool last = (t == nt - 2);
;             const char* a1 = cA + (size_t)(t + 1) * kstep;
;             const char* a2 = last ? nA : cA + (size_t)(t + 2) * kstep; const char* b2 = last ? nB : cB + (size_t)(t + 2) * kstep;
;     ...
;             PG8_LDB(B0, 1, 0); PG8_LDB(B1, 1, 1); PG8_SCHED; PG8_LDA(At, 1, 0); PG8_STAGE(PG8_SA(0, 1), a2 + hstep, voffA);
;             PG8_WAIT_V(8); PG8_WAIT_L(0); PG8_BAR; PG8_MMA(0, 0, At, B0); PG8_MMA(0, 1, At, B1); PG8_BAR; PG8_SCHED;
;             PG8_LDA(At, 1, 1); PG8_STAGE(PG8_SB(1, 0), b3, voffB); PG8_STAGE(PG8_SB(1, 1), b3 + hstep, voffB); PG8_STAGE(PG8_SA(1, 0), a3, voffA);
;             PG8_WAIT_V(8); PG8_WAIT_L(0); PG8_BAR; PG8_MMA(1, 0, At, B0); PG8_MMA(1, 1, At, B1); PG8_BAR; PG8_SCHED;
	s_add_i32 s64, 0, 0x18000
	s_add_i32 s65, 0, 0x1c000
	v_add_u32_e32 v140, s64, v247
	v_add_u32_e32 v156, s65, v247
	ds_read_b128 v[64:67], v140
	ds_read_b128 v[68:71], v140 offset:1024
	ds_read_b128 v[136:139], v140 offset:2048
	ds_read_b128 v[140:143], v140 offset:3072
	ds_read_b128 v[144:147], v156
	ds_read_b128 v[148:151], v156 offset:1024
	ds_read_b128 v[152:155], v156 offset:2048
	ds_read_b128 v[156:159], v156 offset:3072
	s_add_u32 s18, s58, 0x40000
	s_addc_u32 s19, s59, 0
	s_mov_b32 m0, s16
	ds_read_b128 v[160:163], v245 offset:32768
	ds_read_b128 v[164:167], v245 offset:33792
	ds_read_b128 v[168:171], v245 offset:34816
	ds_read_b128 v[172:175], v245 offset:35840
	ds_read_b128 v[176:179], v245 offset:36864
	ds_read_b128 v[180:183], v245 offset:37888
	ds_read_b128 v[184:187], v245 offset:38912
	ds_read_b128 v[188:191], v245 offset:39936
	global_load_lds_dwordx4 v216, s[18:19]
	s_mov_b32 m0, s83
	s_nop 0
	global_load_lds_dwordx4 v220, s[18:19]
	s_waitcnt vmcnt(8)
	s_waitcnt lgkmcnt(0)
	s_barrier
	s_setprio 1
	v_mfma_f32_16x16x32_bf16 v[132:135], v[64:67], v[160:163], v[132:135]
	v_mfma_f32_16x16x32_bf16 v[128:131], v[136:139], v[160:163], v[128:131]
	v_mfma_f32_16x16x32_bf16 v[116:119], v[64:67], v[168:171], v[116:119]
	v_mfma_f32_16x16x32_bf16 v[108:111], v[136:139], v[168:171], v[108:111]
	v_mfma_f32_16x16x32_bf16 v[100:103], v[64:67], v[176:179], v[100:103]
	v_mfma_f32_16x16x32_bf16 v[92:95], v[136:139], v[176:179], v[92:95]
	v_mfma_f32_16x16x32_bf16 v[84:87], v[64:67], v[184:187], v[84:87]
	v_mfma_f32_16x16x32_bf16 v[76:79], v[136:139], v[184:187], v[76:79]
	v_mfma_f32_16x16x32_bf16 v[132:135], v[68:71], v[164:167], v[132:135]
	v_mfma_f32_16x16x32_bf16 v[128:131], v[140:143], v[164:167], v[128:131]
	v_mfma_f32_16x16x32_bf16 v[116:119], v[68:71], v[172:175], v[116:119]
	v_mfma_f32_16x16x32_bf16 v[108:111], v[140:143], v[172:175], v[108:111]
	v_mfma_f32_16x16x32_bf16 v[100:103], v[68:71], v[180:183], v[100:103]
	v_mfma_f32_16x16x32_bf16 v[92:95], v[140:143], v[180:183], v[92:95]
	v_mfma_f32_16x16x32_bf16 v[84:87], v[68:71], v[188:191], v[84:87]
	v_mfma_f32_16x16x32_bf16 v[76:79], v[140:143], v[188:191], v[76:79]
	v_mfma_f32_16x16x32_bf16 v[124:127], v[144:147], v[160:163], v[124:127]
	v_mfma_f32_16x16x32_bf16 v[120:123], v[152:155], v[160:163], v[120:123]
	v_mfma_f32_16x16x32_bf16 v[112:115], v[144:147], v[168:171], v[112:115]
	v_mfma_f32_16x16x32_bf16 v[104:107], v[152:155], v[168:171], v[104:107]
	v_mfma_f32_16x16x32_bf16 v[96:99], v[144:147], v[176:179], v[96:99]
	v_mfma_f32_16x16x32_bf16 v[88:91], v[152:155], v[176:179], v[88:91]
	v_mfma_f32_16x16x32_bf16 v[80:83], v[144:147], v[184:187], v[80:83]
	v_mfma_f32_16x16x32_bf16 v[72:75], v[152:155], v[184:187], v[72:75]
	v_mfma_f32_16x16x32_bf16 v[124:127], v[148:151], v[164:167], v[124:127]
	v_mfma_f32_16x16x32_bf16 v[120:123], v[156:159], v[164:167], v[120:123]
	v_mfma_f32_16x16x32_bf16 v[112:115], v[148:151], v[172:175], v[112:115]
	v_mfma_f32_16x16x32_bf16 v[104:107], v[156:159], v[172:175], v[104:107]
	v_mfma_f32_16x16x32_bf16 v[96:99], v[148:151], v[180:183], v[96:99]
	v_mfma_f32_16x16x32_bf16 v[88:91], v[156:159], v[180:183], v[88:91]
	v_mfma_f32_16x16x32_bf16 v[80:83], v[148:151], v[188:191], v[80:83]
	v_mfma_f32_16x16x32_bf16 v[72:75], v[156:159], v[188:191], v[72:75]
	s_setprio 0
	s_barrier
	s_add_i32 s18, s64, s95
	s_add_i32 m0, s18, 0xffffff80
	ds_read_b128 v[160:163], v245 offset:49152
	ds_read_b128 v[164:167], v245 offset:50176
	ds_read_b128 v[168:171], v245 offset:51200
	ds_read_b128 v[172:175], v245 offset:52224
	ds_read_b128 v[176:179], v245 offset:53248
	ds_read_b128 v[180:183], v245 offset:54272
	ds_read_b128 v[184:187], v245 offset:55296
	ds_read_b128 v[188:191], v245 offset:56320
	global_load_lds_dwordx4 v218, s[56:57] offset:128
	s_add_i32 m0, s18, 0x1f80
	s_add_u32 s18, s56, 0x40080
	s_addc_u32 s19, s57, 0
	global_load_lds_dwordx4 v222, s[56:57] offset:128
	s_add_i32 s56, s65, s95
	s_mov_b32 m0, s56
	s_nop 0
	global_load_lds_dwordx4 v218, s[18:19]
	s_add_i32 m0, s56, 0x2000
	s_nop 0
	global_load_lds_dwordx4 v222, s[18:19]
	s_add_i32 m0, s17, 0xffffff80
	s_nop 0
	global_load_lds_dwordx4 v216, s[58:59] offset:128
	s_add_i32 m0, s23, 0xffffff80
	s_nop 0
	global_load_lds_dwordx4 v220, s[58:59] offset:128
	s_waitcnt vmcnt(8)
	s_waitcnt lgkmcnt(0)
	s_barrier
	s_setprio 1
	v_mfma_f32_16x16x32_bf16 v[60:63], v[64:67], v[160:163], v[60:63]
	v_mfma_f32_16x16x32_bf16 v[52:55], v[136:139], v[160:163], v[52:55]
	v_mfma_f32_16x16x32_bf16 v[44:47], v[64:67], v[168:171], v[44:47]
	v_mfma_f32_16x16x32_bf16 v[36:39], v[136:139], v[168:171], v[36:39]
	v_mfma_f32_16x16x32_bf16 v[28:31], v[64:67], v[176:179], v[28:31]
	v_mfma_f32_16x16x32_bf16 v[20:23], v[136:139], v[176:179], v[20:23]
	v_mfma_f32_16x16x32_bf16 v[12:15], v[64:67], v[184:187], v[12:15]
	v_mfma_f32_16x16x32_bf16 v[4:7], v[136:139], v[184:187], v[4:7]
	v_mfma_f32_16x16x32_bf16 v[60:63], v[68:71], v[164:167], v[60:63]
	v_mfma_f32_16x16x32_bf16 v[52:55], v[140:143], v[164:167], v[52:55]
	v_mfma_f32_16x16x32_bf16 v[44:47], v[68:71], v[172:175], v[44:47]
	v_mfma_f32_16x16x32_bf16 v[36:39], v[140:143], v[172:175], v[36:39]
	v_mfma_f32_16x16x32_bf16 v[28:31], v[68:71], v[180:183], v[28:31]
	v_mfma_f32_16x16x32_bf16 v[20:23], v[140:143], v[180:183], v[20:23]
	v_mfma_f32_16x16x32_bf16 v[12:15], v[68:71], v[188:191], v[12:15]
	v_mfma_f32_16x16x32_bf16 v[4:7], v[140:143], v[188:191], v[4:7]
	v_mfma_f32_16x16x32_bf16 v[56:59], v[144:147], v[160:163], v[56:59]
	v_mfma_f32_16x16x32_bf16 v[48:51], v[152:155], v[160:163], v[48:51]
	v_mfma_f32_16x16x32_bf16 v[40:43], v[144:147], v[168:171], v[40:43]
	v_mfma_f32_16x16x32_bf16 v[32:35], v[152:155], v[168:171], v[32:35]
	v_mfma_f32_16x16x32_bf16 v[24:27], v[144:147], v[176:179], v[24:27]
	v_mfma_f32_16x16x32_bf16 v[16:19], v[152:155], v[176:179], v[16:19]
	v_mfma_f32_16x16x32_bf16 v[8:11], v[144:147], v[184:187], v[8:11]
	v_mfma_f32_16x16x32_bf16 v[0:3], v[152:155], v[184:187], v[0:3]
	v_mfma_f32_16x16x32_bf16 v[56:59], v[148:151], v[164:167], v[56:59]
	v_mfma_f32_16x16x32_bf16 v[48:51], v[156:159], v[164:167], v[48:51]
	v_mfma_f32_16x16x32_bf16 v[40:43], v[148:151], v[172:175], v[40:43]
	v_mfma_f32_16x16x32_bf16 v[32:35], v[156:159], v[172:175], v[32:35]
	v_mfma_f32_16x16x32_bf16 v[24:27], v[148:151], v[180:183], v[24:27]
	v_mfma_f32_16x16x32_bf16 v[16:19], v[156:159], v[180:183], v[16:19]
	v_mfma_f32_16x16x32_bf16 v[8:11], v[148:151], v[188:191], v[8:11]
	v_mfma_f32_16x16x32_bf16 v[0:3], v[156:159], v[188:191], v[0:3]
	s_setprio 0
	s_add_i32 s63, s63, 2
	s_add_u32 s10, s10, 0x100
	s_addc_u32 s11, s11, 0
	s_add_u32 s61, s61, 0x100
	s_addc_u32 s62, s62, 0
	s_cmp_gt_u32 s63, 13
	s_cbranch_scc1 .Lgk1140_exit
	s_add_u32 s18, s10, 0xfffc0080
	s_addc_u32 s19, s11, -1
	s_add_i32 s64, 0, 0x10000
	s_cmp_eq_u32 s63, 12
	s_cselect_b32 s59, s9, s19
	s_cselect_b32 s58, s49, s18
	s_cselect_b32 s57, s47, s62
	s_cselect_b32 s56, s60, s61
	s_add_i32 s65, 0, 0x14000
	v_add_u32_e32 v140, s64, v247
	v_add_u32_e32 v156, s65, v247
	s_barrier
	s_branch .LBB0_1140
; #define PG8_BAR __builtin_amdgcn_s_barrier()
; template <class Epi, class Sched, bool ALIGN_EPI = false, bool SP2 = false>
; __device__ __forceinline__ void gemm_phase(PG8_LAS unsigned char* lds, const Gemm g, const Sched& S, const Epi& E, const int wave0) {
;     ...
;         }
;         if constexpr (ALIGN_EPI) { if (wr == 0) PG8_BAR; }
;         if constexpr (!Epi::AFTER_DRAIN) { E(acc, cur, wr, wc, fr, fq); S.done(cur); }
.Lgk1140_exit:
	s_barrier
	s_and_b64 vcc, exec, s[66:67]
	s_cbranch_vccz .LBB0_1143
	s_barrier
